# v24: + P0b fold loop software-pipelined
# speedup vs baseline: 1.0908x; 1.0043x over previous
.LBB0_106:
	s_lshl_b32 s4, s2, 5
	s_ashr_i32 s28, s2, 5
	s_and_b32 s4, s4, 0x3e0
	s_lshl_b32 s8, s28, 7
	v_or_b32_e32 v10, s4, v1
	s_ashr_i32 s9, s8, 31
	v_mad_u64_u32 v[8:9], s[18:19], v10, s3, v[4:5]
	s_lshl_b64 s[18:19], s[8:9], 2
	s_nop 0
	v_lshl_add_u64 v[8:9], v[8:9], 0, s[18:19]
	v_lshl_add_u64 v[8:9], v[8:9], 0, v[6:7]
	v_add_co_u32_e32 v8, vcc, 0x1000, v8
	v_or_b32_e32 v20, s4, v34
	s_nop 0
	v_addc_co_u32_e32 v9, vcc, 0, v9, vcc
	global_load_dword v12, v[8:9], off offset:1024
	v_lshlrev_b32_e32 v8, 2, v10
	v_or_b32_e32 v10, s4, v28
	global_load_dword v13, v8, s[16:17]
	v_mad_u64_u32 v[8:9], s[24:25], v10, s3, v[4:5]
	v_lshl_add_u64 v[8:9], v[8:9], 0, s[18:19]
	v_lshl_add_u64 v[8:9], v[8:9], 0, v[6:7]
	v_add_co_u32_e32 v8, vcc, 0x1000, v8
	v_add_u32_e32 v40, s4, v37
	s_nop 0
	v_addc_co_u32_e32 v9, vcc, 0, v9, vcc
	global_load_dword v14, v[8:9], off offset:1024
	v_lshlrev_b32_e32 v8, 2, v10
	global_load_dword v15, v8, s[16:17]
	v_or_b32_e32 v8, s4, v30
	v_mad_u64_u32 v[8:9], s[24:25], v8, s3, v[4:5]
	v_lshl_add_u64 v[8:9], v[8:9], 0, s[18:19]
	v_lshl_add_u64 v[8:9], v[8:9], 0, v[6:7]
	v_add_co_u32_e32 v8, vcc, 0x1000, v8
	v_or_b32_e32 v10, s4, v31
	s_nop 0
	v_addc_co_u32_e32 v9, vcc, 0, v9, vcc
	global_load_dword v16, v[8:9], off offset:1024
	v_mad_u64_u32 v[8:9], s[24:25], v10, s3, v[4:5]
	v_lshl_add_u64 v[8:9], v[8:9], 0, s[18:19]
	v_lshl_add_u64 v[8:9], v[8:9], 0, v[6:7]
	v_add_co_u32_e32 v8, vcc, 0x1000, v8
	v_add_lshl_u32 v17, v1, s4, 2
	s_nop 0
	v_addc_co_u32_e32 v9, vcc, 0, v9, vcc
	global_load_dword v18, v[8:9], off offset:1024
	v_lshlrev_b32_e32 v8, 2, v10
	global_load_dword v19, v8, s[16:17]
	v_or_b32_e32 v8, s4, v33
	v_mad_u64_u32 v[8:9], s[24:25], v8, s3, v[4:5]
	v_lshl_add_u64 v[8:9], v[8:9], 0, s[18:19]
	v_lshl_add_u64 v[8:9], v[8:9], 0, v[6:7]
	v_mad_u64_u32 v[10:11], s[24:25], v20, s3, v[4:5]
	v_add_co_u32_e32 v8, vcc, 0x1000, v8
	v_lshl_add_u64 v[10:11], v[10:11], 0, s[18:19]
	s_nop 0
	v_addc_co_u32_e32 v9, vcc, 0, v9, vcc
	v_lshl_add_u64 v[10:11], v[10:11], 0, v[6:7]
	v_add_co_u32_e32 v10, vcc, 0x1000, v10
	s_mov_b32 s9, 0
	s_nop 0
	v_addc_co_u32_e32 v11, vcc, 0, v11, vcc
	global_load_dword v21, v[8:9], off offset:1024
	global_load_dword v22, v[10:11], off offset:1024
	v_lshlrev_b32_e32 v8, 2, v20
	global_load_dword v20, v8, s[16:17]
	v_or_b32_e32 v8, s4, v36
	v_mad_u64_u32 v[8:9], s[24:25], v8, s3, v[4:5]
	v_lshl_add_u64 v[8:9], v[8:9], 0, s[18:19]
	v_lshl_add_u64 v[8:9], v[8:9], 0, v[6:7]
	v_mad_u64_u32 v[10:11], s[24:25], v40, s3, v[4:5]
	v_add_co_u32_e32 v8, vcc, 0x1000, v8
	v_lshl_add_u64 v[10:11], v[10:11], 0, s[18:19]
	s_nop 0
	v_addc_co_u32_e32 v9, vcc, 0, v9, vcc
	v_lshl_add_u64 v[10:11], v[10:11], 0, v[6:7]
	global_load_dword v23, v17, s[16:17] offset:32
	global_load_dword v39, v17, s[16:17] offset:64
	s_nop 0
	global_load_dword v17, v17, s[16:17] offset:96
	v_add_co_u32_e32 v10, vcc, 0x1000, v10
	s_nop 1
	v_addc_co_u32_e32 v11, vcc, 0, v11, vcc
	global_load_dword v8, v[8:9], off offset:1024
	s_nop 0
	global_load_dword v9, v[10:11], off offset:1024
	v_lshlrev_b32_e32 v10, 2, v40
	global_load_dword v10, v10, s[16:17]
	s_waitcnt vmcnt(14)
	v_mul_f32_e32 v11, v12, v13
	ds_write_b32 v27, v11
	v_mov_b32_e32 v12, 0
	v_mov_b32_e32 v13, v3
	s_waitcnt vmcnt(12)
	v_mul_f32_e32 v11, v14, v15
	ds_write_b32 v29, v11
	v_mov_b32_e32 v14, 0
	v_mov_b32_e32 v15, v3
	s_waitcnt vmcnt(5)
	v_mul_f32_e32 v11, v16, v23
	ds_write_b32 v27, v11 offset:32
	v_mul_f32_e32 v11, v18, v19
	ds_write_b32 v32, v11
	s_waitcnt vmcnt(4)
	v_mul_f32_e32 v11, v21, v39
	ds_write_b32 v27, v11 offset:64
	v_mul_f32_e32 v11, v22, v20
	s_waitcnt vmcnt(2)
	v_mul_f32_e32 v8, v8, v17
	ds_write_b32 v35, v11
	ds_write_b32 v27, v8 offset:96
	s_waitcnt vmcnt(0)
	v_mul_f32_e32 v8, v9, v10
	ds_write_b32 v38, v8
	v_lshl_or_b32 v39, s28, 14, v0
	v_mov_b32_e32 v16, 0
	v_mov_b32_e32 v17, v3
	v_mov_b32_e32 v18, 0
	v_mov_b32_e32 v19, v3
	v_mov_b32_e32 v20, 0
	v_mov_b32_e32 v21, v3
	v_mov_b32_e32 v22, 0
	v_mov_b32_e32 v23, v3
	v_mov_b32_e32 v8, 0
	v_mov_b32_e32 v9, v3
	v_mov_b32_e32 v10, 0
	v_mov_b32_e32 v11, v3
	s_waitcnt lgkmcnt(0)
	s_barrier
	v_mov_b32_e32 v88, v39
	v_ashrrev_i32_e32 v89, 31, v39
	v_lshl_add_u64 v[88:89], v[88:89], 2, s[0:1]
	s_mov_b64 s[44:45], 0x40000
	s_mov_b64 s[46:47], 0x800
	v_lshl_add_u64 v[90:91], v[88:89], 0, s[44:45]
	global_load_dword v72, v[88:89], off
	global_load_dword v74, v[90:91], off
	global_load_dword v76, v[88:89], off offset:512
	global_load_dword v78, v[90:91], off offset:512
	global_load_dword v80, v[88:89], off offset:1024
	global_load_dword v82, v[90:91], off offset:1024
	global_load_dword v84, v[88:89], off offset:1536
	global_load_dword v86, v[90:91], off offset:1536
.Lp0b_loop:
	v_lshl_add_u64 v[88:89], v[88:89], 0, s[46:47]
	v_lshl_add_u64 v[90:91], v[90:91], 0, s[46:47]
	global_load_dword v92, v[88:89], off
	global_load_dword v94, v[90:91], off
	global_load_dword v96, v[88:89], off offset:512
	global_load_dword v98, v[90:91], off offset:512
	global_load_dword v100, v[88:89], off offset:1024
	global_load_dword v102, v[90:91], off offset:1024
	global_load_dword v104, v[88:89], off offset:1536
	global_load_dword v106, v[90:91], off offset:1536
	v_add_u32_e32 v68, s9, v24
	ds_read_b128 v[40:43], v68
	ds_read_b128 v[44:47], v68 offset:16
	ds_read_b128 v[48:51], v68 offset:128
	ds_read_b128 v[52:55], v68 offset:144
	ds_read_b128 v[56:59], v68 offset:256
	ds_read_b128 v[60:63], v68 offset:272
	ds_read_b128 v[64:67], v68 offset:384
	ds_read_b128 v[68:71], v68 offset:400
	s_addk_i32 s9, 0x200
	s_waitcnt vmcnt(15) lgkmcnt(7)
	v_pk_fma_f32 v[22:23], v[72:73], v[40:41], v[22:23] op_sel_hi:[0,1,1]
	v_pk_fma_f32 v[20:21], v[72:73], v[42:43], v[20:21] op_sel_hi:[0,1,1]
	s_waitcnt lgkmcnt(6)
	v_pk_fma_f32 v[18:19], v[72:73], v[44:45], v[18:19] op_sel_hi:[0,1,1]
	v_pk_fma_f32 v[16:17], v[72:73], v[46:47], v[16:17] op_sel_hi:[0,1,1]
	s_waitcnt vmcnt(14)
	v_pk_fma_f32 v[14:15], v[74:75], v[40:41], v[14:15] op_sel_hi:[0,1,1]
	v_pk_fma_f32 v[12:13], v[74:75], v[42:43], v[12:13] op_sel_hi:[0,1,1]
	v_pk_fma_f32 v[10:11], v[74:75], v[44:45], v[10:11] op_sel_hi:[0,1,1]
	v_pk_fma_f32 v[8:9], v[74:75], v[46:47], v[8:9] op_sel_hi:[0,1,1]
	s_waitcnt vmcnt(13) lgkmcnt(5)
	v_pk_fma_f32 v[22:23], v[76:77], v[48:49], v[22:23] op_sel_hi:[0,1,1]
	v_pk_fma_f32 v[20:21], v[76:77], v[50:51], v[20:21] op_sel_hi:[0,1,1]
	s_waitcnt lgkmcnt(4)
	v_pk_fma_f32 v[18:19], v[76:77], v[52:53], v[18:19] op_sel_hi:[0,1,1]
	v_pk_fma_f32 v[16:17], v[76:77], v[54:55], v[16:17] op_sel_hi:[0,1,1]
	s_waitcnt vmcnt(12)
	v_pk_fma_f32 v[14:15], v[78:79], v[48:49], v[14:15] op_sel_hi:[0,1,1]
	v_pk_fma_f32 v[12:13], v[78:79], v[50:51], v[12:13] op_sel_hi:[0,1,1]
	v_pk_fma_f32 v[10:11], v[78:79], v[52:53], v[10:11] op_sel_hi:[0,1,1]
	v_pk_fma_f32 v[8:9], v[78:79], v[54:55], v[8:9] op_sel_hi:[0,1,1]
	s_waitcnt vmcnt(11) lgkmcnt(3)
	v_pk_fma_f32 v[22:23], v[80:81], v[56:57], v[22:23] op_sel_hi:[0,1,1]
	v_pk_fma_f32 v[20:21], v[80:81], v[58:59], v[20:21] op_sel_hi:[0,1,1]
	s_waitcnt lgkmcnt(2)
	v_pk_fma_f32 v[18:19], v[80:81], v[60:61], v[18:19] op_sel_hi:[0,1,1]
	v_pk_fma_f32 v[16:17], v[80:81], v[62:63], v[16:17] op_sel_hi:[0,1,1]
	s_waitcnt vmcnt(10)
	v_pk_fma_f32 v[14:15], v[82:83], v[56:57], v[14:15] op_sel_hi:[0,1,1]
	v_pk_fma_f32 v[12:13], v[82:83], v[58:59], v[12:13] op_sel_hi:[0,1,1]
	v_pk_fma_f32 v[10:11], v[82:83], v[60:61], v[10:11] op_sel_hi:[0,1,1]
	v_pk_fma_f32 v[8:9], v[82:83], v[62:63], v[8:9] op_sel_hi:[0,1,1]
	s_waitcnt vmcnt(9) lgkmcnt(1)
	v_pk_fma_f32 v[22:23], v[84:85], v[64:65], v[22:23] op_sel_hi:[0,1,1]
	v_pk_fma_f32 v[20:21], v[84:85], v[66:67], v[20:21] op_sel_hi:[0,1,1]
	s_waitcnt lgkmcnt(0)
	v_pk_fma_f32 v[18:19], v[84:85], v[68:69], v[18:19] op_sel_hi:[0,1,1]
	v_pk_fma_f32 v[16:17], v[84:85], v[70:71], v[16:17] op_sel_hi:[0,1,1]
	s_waitcnt vmcnt(8)
	v_pk_fma_f32 v[14:15], v[86:87], v[64:65], v[14:15] op_sel_hi:[0,1,1]
	v_pk_fma_f32 v[12:13], v[86:87], v[66:67], v[12:13] op_sel_hi:[0,1,1]
	v_pk_fma_f32 v[10:11], v[86:87], v[68:69], v[10:11] op_sel_hi:[0,1,1]
	v_pk_fma_f32 v[8:9], v[86:87], v[70:71], v[8:9] op_sel_hi:[0,1,1]
	v_lshl_add_u64 v[88:89], v[88:89], 0, s[46:47]
	v_lshl_add_u64 v[90:91], v[90:91], 0, s[46:47]
	global_load_dword v72, v[88:89], off
	global_load_dword v74, v[90:91], off
	global_load_dword v76, v[88:89], off offset:512
	global_load_dword v78, v[90:91], off offset:512
	global_load_dword v80, v[88:89], off offset:1024
	global_load_dword v82, v[90:91], off offset:1024
	global_load_dword v84, v[88:89], off offset:1536
	global_load_dword v86, v[90:91], off offset:1536
	v_add_u32_e32 v68, s9, v24
	ds_read_b128 v[40:43], v68
	ds_read_b128 v[44:47], v68 offset:16
	ds_read_b128 v[48:51], v68 offset:128
	ds_read_b128 v[52:55], v68 offset:144
	ds_read_b128 v[56:59], v68 offset:256
	ds_read_b128 v[60:63], v68 offset:272
	ds_read_b128 v[64:67], v68 offset:384
	ds_read_b128 v[68:71], v68 offset:400
	s_addk_i32 s9, 0x200
	s_waitcnt vmcnt(15) lgkmcnt(7)
	v_pk_fma_f32 v[22:23], v[92:93], v[40:41], v[22:23] op_sel_hi:[0,1,1]
	v_pk_fma_f32 v[20:21], v[92:93], v[42:43], v[20:21] op_sel_hi:[0,1,1]
	s_waitcnt lgkmcnt(6)
	v_pk_fma_f32 v[18:19], v[92:93], v[44:45], v[18:19] op_sel_hi:[0,1,1]
	v_pk_fma_f32 v[16:17], v[92:93], v[46:47], v[16:17] op_sel_hi:[0,1,1]
	s_waitcnt vmcnt(14)
	v_pk_fma_f32 v[14:15], v[94:95], v[40:41], v[14:15] op_sel_hi:[0,1,1]
	v_pk_fma_f32 v[12:13], v[94:95], v[42:43], v[12:13] op_sel_hi:[0,1,1]
	v_pk_fma_f32 v[10:11], v[94:95], v[44:45], v[10:11] op_sel_hi:[0,1,1]
	v_pk_fma_f32 v[8:9], v[94:95], v[46:47], v[8:9] op_sel_hi:[0,1,1]
	s_waitcnt vmcnt(13) lgkmcnt(5)
	v_pk_fma_f32 v[22:23], v[96:97], v[48:49], v[22:23] op_sel_hi:[0,1,1]
	v_pk_fma_f32 v[20:21], v[96:97], v[50:51], v[20:21] op_sel_hi:[0,1,1]
	s_waitcnt lgkmcnt(4)
	v_pk_fma_f32 v[18:19], v[96:97], v[52:53], v[18:19] op_sel_hi:[0,1,1]
	v_pk_fma_f32 v[16:17], v[96:97], v[54:55], v[16:17] op_sel_hi:[0,1,1]
	s_waitcnt vmcnt(12)
	v_pk_fma_f32 v[14:15], v[98:99], v[48:49], v[14:15] op_sel_hi:[0,1,1]
	v_pk_fma_f32 v[12:13], v[98:99], v[50:51], v[12:13] op_sel_hi:[0,1,1]
	v_pk_fma_f32 v[10:11], v[98:99], v[52:53], v[10:11] op_sel_hi:[0,1,1]
	v_pk_fma_f32 v[8:9], v[98:99], v[54:55], v[8:9] op_sel_hi:[0,1,1]
	s_waitcnt vmcnt(11) lgkmcnt(3)
	v_pk_fma_f32 v[22:23], v[100:101], v[56:57], v[22:23] op_sel_hi:[0,1,1]
	v_pk_fma_f32 v[20:21], v[100:101], v[58:59], v[20:21] op_sel_hi:[0,1,1]
	s_waitcnt lgkmcnt(2)
	v_pk_fma_f32 v[18:19], v[100:101], v[60:61], v[18:19] op_sel_hi:[0,1,1]
	v_pk_fma_f32 v[16:17], v[100:101], v[62:63], v[16:17] op_sel_hi:[0,1,1]
	s_waitcnt vmcnt(10)
	v_pk_fma_f32 v[14:15], v[102:103], v[56:57], v[14:15] op_sel_hi:[0,1,1]
	v_pk_fma_f32 v[12:13], v[102:103], v[58:59], v[12:13] op_sel_hi:[0,1,1]
	v_pk_fma_f32 v[10:11], v[102:103], v[60:61], v[10:11] op_sel_hi:[0,1,1]
	v_pk_fma_f32 v[8:9], v[102:103], v[62:63], v[8:9] op_sel_hi:[0,1,1]
	s_waitcnt vmcnt(9) lgkmcnt(1)
	v_pk_fma_f32 v[22:23], v[104:105], v[64:65], v[22:23] op_sel_hi:[0,1,1]
	v_pk_fma_f32 v[20:21], v[104:105], v[66:67], v[20:21] op_sel_hi:[0,1,1]
	s_waitcnt lgkmcnt(0)
	v_pk_fma_f32 v[18:19], v[104:105], v[68:69], v[18:19] op_sel_hi:[0,1,1]
	v_pk_fma_f32 v[16:17], v[104:105], v[70:71], v[16:17] op_sel_hi:[0,1,1]
	s_waitcnt vmcnt(8)
	v_pk_fma_f32 v[14:15], v[106:107], v[64:65], v[14:15] op_sel_hi:[0,1,1]
	v_pk_fma_f32 v[12:13], v[106:107], v[66:67], v[12:13] op_sel_hi:[0,1,1]
	v_pk_fma_f32 v[10:11], v[106:107], v[68:69], v[10:11] op_sel_hi:[0,1,1]
	v_pk_fma_f32 v[8:9], v[106:107], v[70:71], v[8:9] op_sel_hi:[0,1,1]
	s_cmpk_eq_i32 s9, 0x4000
	s_cbranch_scc0 .Lp0b_loop
	s_waitcnt vmcnt(0)
	v_cvt_pk_bf16_f32 v43, v16, v17
	v_add_u32_e32 v16, s8, v25
	v_ashrrev_i32_e32 v17, 31, v16
	v_lshlrev_b64 v[16:17], 11, v[16:17]
	v_lshl_add_u64 v[16:17], s[48:49], 0, v[16:17]
	s_lshl_b32 s4, s4, 1
	v_lshl_add_u64 v[16:17], v[16:17], 0, s[4:5]
	v_cvt_pk_bf16_f32 v40, v22, v23
	v_cvt_pk_bf16_f32 v41, v20, v21
	v_cvt_pk_bf16_f32 v42, v18, v19
	v_lshl_add_u64 v[16:17], v[16:17], 0, v[2:3]
	global_store_dwordx4 v[16:17], v[40:43], off
	v_cvt_pk_bf16_f32 v17, v8, v9
	v_add_u32_e32 v8, s8, v26
	v_ashrrev_i32_e32 v9, 31, v8
	v_lshlrev_b64 v[8:9], 11, v[8:9]
	v_lshl_add_u64 v[8:9], s[48:49], 0, v[8:9]
	v_lshl_add_u64 v[8:9], v[8:9], 0, s[4:5]
	s_add_i32 s2, s2, s54
	v_cvt_pk_bf16_f32 v14, v14, v15
	v_cvt_pk_bf16_f32 v15, v12, v13
	v_cvt_pk_bf16_f32 v16, v10, v11
	v_lshl_add_u64 v[8:9], v[8:9], 0, v[2:3]
	s_cmpk_gt_i32 s2, 0x7f
	global_store_dwordx4 v[8:9], v[14:17], off
	s_barrier
	s_cbranch_scc0 .LBB0_106
